# attention epilogue touches the next unit's Q rows (prefetch into L1/L2) after its output stores
# speedup vs baseline: 1.0046x; 1.0046x over previous
.LBB0_218:
	s_or_b64 exec, exec, s[2:3]
	v_mov_b32_e32 v32, v121
	v_readlane_b32 s2, v254, 53
	s_nop 1
	v_mov_b32_e32 v92, s2
	ds_write_b32 v92, v121 offset:8

.LBB0_221:
	s_or_b64 exec, exec, s[0:1]
	s_waitcnt lgkmcnt(0)
	v_lshl_add_u32 v34, v151, 2, s79
	ds_read_b128 v[38:41], v34
	ds_read_b128 v[42:45], v34 offset:32
	ds_read_b128 v[46:49], v34 offset:64
	ds_read_b128 v[50:53], v34 offset:96
	v_lshlrev_b32_e32 v90, 4, v148
	v_and_b32_e32 v90, 48, v90
	v_lshlrev_b32_e32 v90, 2, v90
	global_load_dwordx4 v[74:77], v90, s[52:53]
	global_load_dwordx4 v[78:81], v90, s[52:53] offset:32
	global_load_dwordx4 v[82:85], v90, s[52:53] offset:16
	global_load_dwordx4 v[86:89], v90, s[52:53] offset:48
	v_lshlrev_b32_e32 v37, 2, v149
	v_readlane_b32 s0, v251, 19
	s_waitcnt lgkmcnt(0)
	v_readlane_b32 s1, v254, 37
	v_mul_f32_e32 v54, v16, v38
	v_mul_f32_e32 v55, v0, v38
	v_or_b32_e32 v56, s1, v151
	v_mul_u32_u24_e32 v56, 0x110, v56
	v_add3_u32 v56, s0, v56, v37
	ds_write2_b32 v56, v54, v55 offset1:32
	v_readlane_b32 s1, v254, 23
	v_mul_f32_e32 v57, v17, v39
	v_mul_f32_e32 v58, v1, v39
	v_or_b32_e32 v59, s1, v151
	v_mul_u32_u24_e32 v59, 0x110, v59
	v_add3_u32 v59, s0, v59, v37
	ds_write2_b32 v59, v57, v58 offset1:32
	v_readlane_b32 s1, v254, 24
	v_mul_f32_e32 v54, v18, v40
	v_mul_f32_e32 v55, v2, v40
	v_or_b32_e32 v56, s1, v151
	v_mul_u32_u24_e32 v56, 0x110, v56
	v_add3_u32 v56, s0, v56, v37
	ds_write2_b32 v56, v54, v55 offset1:32
	v_readlane_b32 s1, v254, 25
	v_mul_f32_e32 v57, v19, v41
	v_mul_f32_e32 v58, v3, v41
	v_or_b32_e32 v59, s1, v151
	v_mul_u32_u24_e32 v59, 0x110, v59
	v_add3_u32 v59, s0, v59, v37
	ds_write2_b32 v59, v57, v58 offset1:32
	v_readlane_b32 s1, v254, 26
	v_mul_f32_e32 v54, v20, v42
	v_mul_f32_e32 v55, v4, v42
	v_or_b32_e32 v56, s1, v151
	v_mul_u32_u24_e32 v56, 0x110, v56
	v_add3_u32 v56, s0, v56, v37
	ds_write2_b32 v56, v54, v55 offset1:32
	v_readlane_b32 s1, v254, 27
	v_mul_f32_e32 v57, v21, v43
	v_mul_f32_e32 v58, v5, v43
	v_or_b32_e32 v59, s1, v151
	v_mul_u32_u24_e32 v59, 0x110, v59
	v_add3_u32 v59, s0, v59, v37
	ds_write2_b32 v59, v57, v58 offset1:32
	v_readlane_b32 s1, v254, 28
	v_mul_f32_e32 v54, v22, v44
	v_mul_f32_e32 v55, v6, v44
	v_or_b32_e32 v56, s1, v151
	v_mul_u32_u24_e32 v56, 0x110, v56
	v_add3_u32 v56, s0, v56, v37
	ds_write2_b32 v56, v54, v55 offset1:32
	v_readlane_b32 s1, v254, 29
	v_mul_f32_e32 v57, v23, v45
	v_mul_f32_e32 v58, v7, v45
	v_or_b32_e32 v59, s1, v151
	v_mul_u32_u24_e32 v59, 0x110, v59
	v_add3_u32 v59, s0, v59, v37
	ds_write2_b32 v59, v57, v58 offset1:32
	v_readlane_b32 s1, v254, 30
	v_mul_f32_e32 v54, v24, v46
	v_mul_f32_e32 v55, v8, v46
	v_or_b32_e32 v56, s1, v151
	v_mul_u32_u24_e32 v56, 0x110, v56
	v_add3_u32 v56, s0, v56, v37
	ds_write2_b32 v56, v54, v55 offset1:32
	v_readlane_b32 s1, v254, 31
	v_mul_f32_e32 v57, v25, v47
	v_mul_f32_e32 v58, v9, v47
	v_or_b32_e32 v59, s1, v151
	v_mul_u32_u24_e32 v59, 0x110, v59
	v_add3_u32 v59, s0, v59, v37
	ds_write2_b32 v59, v57, v58 offset1:32
	v_readlane_b32 s1, v254, 32
	v_mul_f32_e32 v54, v26, v48
	v_mul_f32_e32 v55, v10, v48
	v_or_b32_e32 v56, s1, v151
	v_mul_u32_u24_e32 v56, 0x110, v56
	v_add3_u32 v56, s0, v56, v37
	ds_write2_b32 v56, v54, v55 offset1:32
	v_readlane_b32 s1, v254, 33
	v_mul_f32_e32 v57, v27, v49
	v_mul_f32_e32 v58, v11, v49
	v_or_b32_e32 v59, s1, v151
	v_mul_u32_u24_e32 v59, 0x110, v59
	v_add3_u32 v59, s0, v59, v37
	ds_write2_b32 v59, v57, v58 offset1:32
	v_readlane_b32 s1, v254, 34
	v_mul_f32_e32 v54, v28, v50
	v_mul_f32_e32 v55, v12, v50
	v_or_b32_e32 v56, s1, v151
	v_mul_u32_u24_e32 v56, 0x110, v56
	v_add3_u32 v56, s0, v56, v37
	ds_write2_b32 v56, v54, v55 offset1:32
	v_readlane_b32 s1, v254, 35
	v_mul_f32_e32 v57, v29, v51
	v_mul_f32_e32 v58, v13, v51
	v_or_b32_e32 v59, s1, v151
	v_mul_u32_u24_e32 v59, 0x110, v59
	v_add3_u32 v59, s0, v59, v37
	ds_write2_b32 v59, v57, v58 offset1:32
	v_readlane_b32 s1, v254, 36
	v_mul_f32_e32 v54, v30, v52
	v_mul_f32_e32 v55, v14, v52
	v_or_b32_e32 v56, s1, v151
	v_mul_u32_u24_e32 v56, 0x110, v56
	v_add3_u32 v56, s0, v56, v37
	ds_write2_b32 v56, v54, v55 offset1:32
	v_readlane_b32 s1, v254, 38
	v_mul_f32_e32 v57, v31, v53
	v_mul_f32_e32 v58, v15, v53
	v_or_b32_e32 v59, s1, v151
	v_mul_u32_u24_e32 v59, 0x110, v59
	v_add3_u32 v59, s0, v59, v37
	ds_write2_b32 v59, v57, v58 offset1:32
	v_ashrrev_i32_e32 v50, 2, v148
	v_lshlrev_b32_e32 v0, 4, v148
	v_and_b32_e32 v52, 48, v0
	v_lshlrev_b32_e32 v16, 2, v52
	s_waitcnt lgkmcnt(0)
	s_barrier
	v_readlane_b32 s2, v254, 53
	s_nop 1
	v_mov_b32_e32 v93, s2
	ds_read_b32 v93, v93 offset:8
	s_movk_i32 s0, 0x110
	v_mul_lo_u32 v17, v50, s0
	v_add3_u32 v46, 0, v17, v16
	ds_read_b128 v[16:19], v46 offset:32
	ds_read_b128 v[20:23], v46 offset:48
	ds_read_b128 v[24:27], v46 offset:34864
	ds_read_b128 v[28:31], v46
	ds_read_b128 v[34:37], v46 offset:16
	ds_read_b128 v[38:41], v46 offset:34832
	ds_read_b128 v[42:45], v46 offset:34848
	ds_read_b128 v[46:49], v46 offset:34816
	s_waitcnt lgkmcnt(5)
	v_pk_fma_f32 v[20:21], v[110:111], v[24:25], v[20:21] neg_lo:[1,0,0] neg_hi:[1,0,0]
	v_pk_fma_f32 v[22:23], v[110:111], v[26:27], v[22:23] neg_lo:[1,0,0] neg_hi:[1,0,0]
	s_waitcnt lgkmcnt(2)
	v_pk_fma_f32 v[34:35], v[110:111], v[38:39], v[34:35] neg_lo:[1,0,0] neg_hi:[1,0,0]
	v_pk_fma_f32 v[36:37], v[110:111], v[40:41], v[36:37] neg_lo:[1,0,0] neg_hi:[1,0,0]
	s_waitcnt lgkmcnt(0)
	v_pk_fma_f32 v[28:29], v[110:111], v[46:47], v[28:29] neg_lo:[1,0,0] neg_hi:[1,0,0]
	v_pk_fma_f32 v[30:31], v[110:111], v[48:49], v[30:31] neg_lo:[1,0,0] neg_hi:[1,0,0]
	v_pk_mul_f32 v[46:47], v[28:29], v[28:29]
	v_pk_mul_f32 v[48:49], v[30:31], v[30:31]
	v_add_f32_e32 v46, v46, v47
	v_add_f32_e32 v46, v46, v48
	v_pk_mul_f32 v[38:39], v[34:35], v[34:35]
	v_add_f32_e32 v46, v46, v49
	v_add_f32_e32 v38, v46, v38
	v_pk_mul_f32 v[40:41], v[36:37], v[36:37]
	v_add_f32_e32 v38, v38, v39
	v_pk_fma_f32 v[16:17], v[110:111], v[42:43], v[16:17] neg_lo:[1,0,0] neg_hi:[1,0,0]
	v_add_f32_e32 v38, v38, v40
	v_pk_mul_f32 v[42:43], v[16:17], v[16:17]
	v_add_f32_e32 v38, v38, v41
	v_pk_fma_f32 v[18:19], v[110:111], v[44:45], v[18:19] neg_lo:[1,0,0] neg_hi:[1,0,0]
	v_add_f32_e32 v38, v38, v42
	v_pk_mul_f32 v[44:45], v[18:19], v[18:19]
	v_add_f32_e32 v38, v38, v43
	v_add_f32_e32 v38, v38, v44
	v_pk_mul_f32 v[24:25], v[20:21], v[20:21]
	v_add_f32_e32 v38, v38, v45
	v_add_f32_e32 v24, v38, v24
	v_pk_mul_f32 v[26:27], v[22:23], v[22:23]
	v_add_f32_e32 v24, v24, v25
	v_add_f32_e32 v24, v24, v26
	v_add_f32_e32 v24, v24, v27
	ds_swizzle_b32 v25, v24 offset:swizzle(SWAP,1)
	s_mov_b32 s0, 0x800000
	v_ashrrev_i32_e32 v51, 31, v50
	s_waitcnt lgkmcnt(0)
	v_add_f32_e32 v24, v24, v25
	ds_swizzle_b32 v25, v24 offset:swizzle(SWAP,2)
	s_waitcnt lgkmcnt(0)
	v_add_f32_e32 v24, v24, v25
	v_mov_b32_e32 v25, 0x3727c5ac
	v_fmamk_f32 v24, v24, 0x3c800000, v25
	v_mul_f32_e32 v25, 0x4b800000, v24
	v_cmp_gt_f32_e32 vcc, s0, v24
	s_add_u32 s0, s37, s33
	s_addc_u32 s1, 0, 0
	v_cndmask_b32_e32 v24, v24, v25, vcc
	v_rsq_f32_e32 v24, v24
	s_nop 0
	v_mul_f32_e32 v25, 0x45800000, v24
	v_cndmask_b32_e32 v24, v24, v25, vcc
	v_mul_f32_e32 v24, v147, v24
	v_pk_mul_f32 v[16:17], v[16:17], v[24:25] op_sel_hi:[1,0]
	v_pk_mul_f32 v[18:19], v[18:19], v[24:25] op_sel_hi:[1,0]
	v_pk_mul_f32 v[26:27], v[28:29], v[24:25] op_sel_hi:[1,0]
	v_pk_mul_f32 v[28:29], v[30:31], v[24:25] op_sel_hi:[1,0]
	v_pk_mul_f32 v[30:31], v[34:35], v[24:25] op_sel_hi:[1,0]
	v_pk_mul_f32 v[34:35], v[36:37], v[24:25] op_sel_hi:[1,0]
	v_pk_mul_f32 v[20:21], v[20:21], v[24:25] op_sel_hi:[1,0]
	s_waitcnt vmcnt(3)
	v_pk_mul_f32 v[0:1], v[74:75], v[26:27]
	s_waitcnt vmcnt(2)
	v_pk_mul_f32 v[4:5], v[78:79], v[16:17]
	v_pk_mul_f32 v[16:17], v[22:23], v[24:25] op_sel_hi:[1,0]
	v_pk_mul_f32 v[6:7], v[80:81], v[18:19]
	s_waitcnt vmcnt(0)
	v_pk_mul_f32 v[14:15], v[16:17], v[88:89]
	v_lshl_add_u64 v[16:17], s[0:1], 0, v[50:51]
	v_readlane_b32 s0, v250, 15
	v_lshlrev_b64 v[16:17], 11, v[16:17]
	v_readlane_b32 s12, v250, 27
	v_readlane_b32 s13, v250, 28
	v_readlane_b32 s1, v250, 16
	v_lshlrev_b32_e32 v18, 1, v52
	v_lshl_add_u64 v[16:17], s[12:13], 0, v[16:17]
	v_lshl_add_u64 v[16:17], v[16:17], 0, s[34:35]
	v_mov_b32_e32 v19, v65
	v_lshl_add_u64 v[16:17], v[16:17], 0, v[18:19]
	s_mov_b64 s[0:1], 0x2000200
	v_pk_mul_f32 v[2:3], v[76:77], v[28:29]
	v_pk_mul_f32 v[8:9], v[82:83], v[30:31]
	v_lshl_add_u64 v[18:19], v[16:17], 0, s[0:1]
	s_brev_b32 s0, 64
	v_pk_mul_f32 v[10:11], v[34:35], v[84:85]
	v_cvt_pk_bf16_f32 v0, v0, v1
	v_cvt_pk_bf16_f32 v1, v2, v3
	v_cvt_pk_bf16_f32 v2, v8, v9
	v_add_co_u32_e32 v8, vcc, s0, v16
	v_pk_mul_f32 v[12:13], v[86:87], v[20:21]
	v_cvt_pk_bf16_f32 v3, v10, v11
	v_addc_co_u32_e32 v9, vcc, 0, v17, vcc
	global_store_dwordx4 v[8:9], v[0:3], off offset:512
	s_mov_b64 s[0:1], 0
	v_readlane_b32 s2, v250, 17
	v_cvt_pk_bf16_f32 v0, v4, v5
	v_cvt_pk_bf16_f32 v1, v6, v7
	v_cvt_pk_bf16_f32 v2, v12, v13
	v_cvt_pk_bf16_f32 v3, v14, v15
	v_readlane_b32 s3, v250, 18
	v_readlane_b32 s4, v250, 19
	v_readlane_b32 s5, v250, 20
	v_readlane_b32 s6, v250, 21
	v_readlane_b32 s7, v250, 22
	v_readlane_b32 s8, v250, 23
	v_readlane_b32 s9, v250, 24
	v_readlane_b32 s10, v250, 25
	v_readlane_b32 s11, v250, 26
	v_readlane_b32 s14, v250, 29
	v_readlane_b32 s15, v250, 30
	global_store_dwordx4 v[18:19], v[0:3], off offset:16
	v_readfirstlane_b32 vcc_lo, v93
	v_lshrrev_b32_e32 v94, 2, v93
	v_and_b32_e32 v95, 15, v93
	v_and_b32_e32 v94, -4, v94
	v_mov_b32_e32 v96, 0x405132
	s_cmpk_gt_u32 vcc_lo, 0x5f
	s_cbranch_scc1 .Lqpf_skip
	v_lshrrev_b32_e32 v94, v94, v96
	v_readlane_b32 vcc_lo, v254, 37
	v_lshlrev_b32_e32 v95, 7, v95
	v_and_b32_e32 v94, 7, v94
	v_readlane_b32 vcc_hi, v251, 13
	v_or_b32_e32 v95, v95, v149
	v_or_b32_e32 v95, vcc_lo, v95
	v_or_b32_e32 v95, s33, v95
	v_lshlrev_b32_e32 v94, 7, v94
	v_bfe_u32 v97, v148, 5, 1
	v_mov_b32_e32 v96, 0x1080
	v_lshl_add_u32 v94, vcc_hi, 1, v94
	v_mov_b64_e32 v[98:99], s[72:73]
	v_lshl_add_u32 v94, v97, 4, v94
	v_mad_u64_u32 v[98:99], vcc, v95, v96, v[98:99]
	v_mov_b32_e32 v95, 0
	s_nop 0
	v_lshl_add_u64 v[98:99], v[98:99], 0, v[94:95]
	global_load_dwordx4 v[74:77], v[98:99], off
	global_load_dwordx4 v[78:81], v[98:99], off offset:32
.Lqpf_skip:
	s_barrier
.LBB0_222:
	s_and_b64 vcc, exec, s[0:1]
	s_cbranch_vccz .LBB0_148
	s_addk_i32 s36, 0xffa0
	s_lshr_b32 s4, s36, 2
	s_and_saveexec_b64 s[0:1], s[40:41]
	s_cbranch_execz .LBB0_228
	s_lshl_b32 s2, s4, 2
	v_readlane_b32 s6, v255, 36
	v_mov_b32_e32 v0, s2
	v_readlane_b32 s7, v255, 37
	s_add_u32 s2, s6, s2
	s_addc_u32 s3, s7, 0
	s_nop 2
	global_load_dword v0, v0, s[6:7] sc1
	s_waitcnt vmcnt(0)
	v_cmp_lt_u32_e32 vcc, 1, v0
	s_cbranch_vccnz .LBB0_227
	s_mov_b32 s5, 0
